# attention half-unit queue split per XCD (each XCD serves two batch-head pairs, K/V rows always through the same L2)
# baseline (speedup 1.0000x reference)
; __device__ __forceinline__ int dq_first(Frame& F, unsigned* q) {
;     if (F.tid == 64) F.MISC[20] = __hip_atomic_fetch_add(q, 1u, __ATOMIC_RELAXED, __HIP_MEMORY_SCOPE_AGENT);
;     __syncthreads();
;     return (int)__builtin_amdgcn_readfirstlane(F.MISC[20]);
; __device__ __forceinline__ void p2_mixers(Frame& F, unsigned* qctr) {
;     ...
;     { unsigned* aq = qctr + 192; int cur = dq_first(F, aq), par = 0;
;       while (cur < 512) {
;           unsigned nxt = 0; if (F.tid == 64) nxt = __hip_atomic_fetch_add(aq, 1u, __ATOMIC_RELAXED, __HIP_MEMORY_SCOPE_AGENT);
.Ldqc_exit:
.LBB0_1420:
	s_waitcnt lgkmcnt(0)
	s_and_b32 s42, s96, 7
	s_lshl_b32 s42, s42, 8
	s_add_u32 s42, s42, 0x1400
	s_add_u32 s42, s26, s42
	s_addc_u32 s43, s27, 0
	v_cmp_eq_u32_e64 s[6:7], 64, v0
	s_and_saveexec_b64 s[8:9], s[6:7]
	s_cbranch_execz .LBB0_1424
	s_mov_b64 s[12:13], exec
	v_mbcnt_lo_u32_b32 v1, s12, 0
	v_mbcnt_hi_u32_b32 v1, s13, v1
	v_cmp_eq_u32_e32 vcc, 0, v1
	s_and_saveexec_b64 s[10:11], vcc
	s_cbranch_execz .LBB0_1423
	s_bcnt1_i32_b64 s2, s[12:13]
	s_waitcnt vmcnt(32)
	v_mov_b32_e32 v2, 0
	v_mov_b32_e32 v3, s2
	global_atomic_add v2, v2, v3, s[42:43] sc0

; #define LAS __attribute__((address_space(3)))
; __device__ __forceinline__ void sb_attn_unit(Frame& F, int b, int h, int qb, int half) {
;     const bf16* Qb = WSP(bf16, WS_Q); const bf16* Kb = WSP(bf16, WS_K); const bf16* Vb = WSP(bf16, WS_V); bf16* MIX = WSP(bf16, WS_MIX);
;     const int lane = F.lane, r32 = lane & 31, hh = lane >> 5;
;     const int q0w = 256 * qb + 32 * F.wave;
;     LAS unsigned char* KB0 = F.lds + RING_OFF; LAS unsigned char* VB0 = F.lds + RING_OFF + 32768;
;     bf16x8 qf[8];
;     { const bf16* qp = Qb + ((size_t)b * T + q0w + r32) * SBW + h * HD + 8 * hh;
; #pragma unroll
;       for (int s = 0; s < 8; ++s) qf[s] = *(const bf16x8*)(qp + 16 * s); }
;     const float k1 = SB_SCALE * LOG2E, k2 = kin(12)[h] * LOG2E;
;     f32x16 oacc[4];
; #pragma unroll
;     for (int d = 0; d < 4; ++d)
; #pragma unroll
;         for (int i = 0; i < 16; ++i) oacc[d][i] = 0.f;
;     float R = 1.f;
;     const int nt = 2 * qb + 2, ktop = (half == 0) ? 4 * qb + 3 : 2 * qb + 1;
;     const int srow = F.tid >> 4, sch = F.tid & 15;
;     const size_t gbase = ((size_t)b * T) * SBW + h * HD + sch * 8;
;     v4u rk[2], rv[2];
;     ...
;     const unsigned kwo = (unsigned)((sch >> 1) * 1024 + srow * 32 + (((sch & 1) ^ ((srow >> 3) & 1)) * 16));
;     const unsigned vwo = (unsigned)((((srow >> 3) * 4 + (sch >> 2)) * 512) + (srow & 7) * 64 + (sch & 3) * 16);
;     ...
;     SB_LOAD(64 * ktop); SB_WRITE(0);
;     __syncthreads();
;     const int tq = (lane & 15) >> 2, tp = lane & 3, tblk = (lane >> 4) & 1;
;     const unsigned kro = (unsigned)(r32 * 32 + ((hh ^ ((r32 >> 3) & 1)) * 16));
;     const unsigned vro = (unsigned)((4 * hh + tq) * 64 + tblk * 32 + tp * 8);
; __device__ __forceinline__ void p2_mixers(Frame& F, unsigned* qctr) {
;     ...
;     { unsigned* aq = qctr + 192; int cur = dq_first(F, aq), par = 0;
;       while (cur < 512) {
;           unsigned nxt = 0; if (F.tid == 64) nxt = __hip_atomic_fetch_add(aq, 1u, __ATOMIC_RELAXED, __HIP_MEMORY_SCOPE_AGENT);
;           const int qb = 15 - (cur >> 5), hf = (cur >> 4) & 1, bh = cur & 15;
;           sb_attn_unit(F, bh >> 3, bh & 7, qb, hf);
;           par ^= 1; if (F.tid == 64) F.MISC[20 + par] = nxt;
;           __syncthreads();
;           cur = (int)__builtin_amdgcn_readfirstlane(F.MISC[20 + par]);
;       } }
.LBB0_1424:
	s_or_b64 exec, exec, s[8:9]
	s_add_i32 s2, 0, 0x25190
	v_mov_b32_e32 v1, s2
	s_waitcnt lgkmcnt(0)
	s_barrier
	ds_read_b32 v1, v1
	s_mov_b32 s45, 0
	s_waitcnt lgkmcnt(0)
	v_readfirstlane_b32 s2, v1
	s_cmpk_gt_i32 s2, 0x3f
	s_cbranch_scc1 .LBB0_1449
	s_waitcnt vmcnt(0)
	v_lshrrev_b32_e32 v8, 7, v0
	v_lshlrev_b32_e32 v6, 9, v0
	v_xor_b32_e32 v9, v8, v0
	v_lshrrev_b32_e32 v157, 4, v0
	v_and_b32_e32 v6, 0x1c00, v6
	v_lshlrev_b32_e32 v9, 4, v9
	v_lshlrev_b32_e32 v10, 7, v0
	v_lshlrev_b32_e32 v7, 5, v157
	v_and_b32_e32 v9, 16, v9
	v_and_b32_e32 v10, 0x600, v10
	v_lshlrev_b32_e32 v12, 4, v0
	v_lshlrev_b32_e32 v8, 11, v8
	v_add_u32_e32 v6, 0, v6
	v_lshrrev_b32_e32 v2, 5, v199
	v_and_b32_e32 v11, 0x1c0, v217
	v_and_b32_e32 v12, 48, v12
	v_add3_u32 v162, v6, v7, v9
	v_add3_u32 v6, 0, v10, v8
	s_add_u32 s46, s26, 0x9480000
	v_add3_u32 v163, v6, v11, v12
	v_lshrrev_b32_e32 v6, 2, v0
	v_lshrrev_b32_e32 v8, 3, v0
	v_lshlrev_b32_e32 v164, 2, v2
	s_addc_u32 s47, s27, 0
	v_lshlrev_b32_e32 v4, 3, v2
	v_lshlrev_b32_e32 v5, 3, v0
	v_bitop3_b32 v8, v8, v2, 1 bitop3:0x6c
	v_and_or_b32 v2, v6, 3, v164
	v_lshlrev_b32_e32 v6, 1, v0
	s_add_u32 s48, s26, 0xa480000
	v_and_b32_e32 v150, 0x78, v5
	v_and_b32_e32 v6, 32, v6
	v_and_b32_e32 v5, 24, v5
	v_lshl_add_u32 v2, v2, 6, 0
	s_addc_u32 s49, s27, 0
	v_mov_b32_e32 v3, 0
	v_lshlrev_b32_e32 v7, 5, v182
	v_lshlrev_b32_e32 v8, 4, v8
	v_add3_u32 v166, v2, v6, v5
	v_lshlrev_b32_e32 v2, 2, v199
	s_add_u32 s50, s26, 0xb480000
	v_add3_u32 v165, 0, v7, v8
	v_lshl_add_u64 v[6:7], s[26:27], 0, v[2:3]
	s_mov_b64 s[10:11], 0x3508b000
	v_mbcnt_lo_u32_b32 v2, -1, 0
	s_addc_u32 s51, s27, 0
	v_mov_b32_e32 v1, v3
	v_cmp_gt_u32_e64 s[8:9], 32, v199
	v_lshl_add_u64 v[152:153], v[6:7], 0, s[10:11]
	v_lshlrev_b32_e32 v154, 1, v4
	v_mov_b32_e32 v155, v3
	s_movk_i32 s22, 0x1000
	v_mbcnt_hi_u32_b32 v167, -1, v2
	v_mov_b32_e32 v168, 0x2100
	s_mov_b32 s28, 0
	s_branch .LBB0_1427
.LBB0_1426:
	s_or_b64 exec, exec, s[10:11]
	s_lshl_b32 s2, s28, 2
	s_add_i32 s2, s2, 0
	s_add_i32 s2, s2, 0x25190
	v_mov_b32_e32 v2, s2
	s_waitcnt lgkmcnt(0)
	s_barrier
	ds_read_b32 v2, v2
	s_waitcnt lgkmcnt(0)
	v_readfirstlane_b32 s2, v2
	s_cmpk_lt_i32 s2, 0x40
	s_cbranch_scc0 .LBB0_1449

; #define LAS __attribute__((address_space(3)))
; #define SB_LOAD(k0_) do { _Pragma("unroll") for (int i_ = 0; i_ < 2; ++i_) { const size_t o_ = gbase + (size_t)((k0_) + srow + 32 * i_) * SBW; rk[i_] = *(const v4u*)(Kb + o_); rv[i_] = *(const v4u*)(Vb + o_); } } while (0)
; #define SB_WRITE(buf_) do { _Pragma("unroll") for (int i_ = 0; i_ < 2; ++i_) { *(LAS v4u*)(KB0 + (buf_) * 16384 + kwo + i_ * 8192) = rk[i_]; *(LAS v4u*)(VB0 + (buf_) * 16384 + vwo + i_ * 8192) = rv[i_]; } } while (0)
; __device__ __forceinline__ void sb_attn_unit(Frame& F, int b, int h, int qb, int half) {
;     const bf16* Qb = WSP(bf16, WS_Q); const bf16* Kb = WSP(bf16, WS_K); const bf16* Vb = WSP(bf16, WS_V); bf16* MIX = WSP(bf16, WS_MIX);
;     const int lane = F.lane, r32 = lane & 31, hh = lane >> 5;
;     const int q0w = 256 * qb + 32 * F.wave;
;     LAS unsigned char* KB0 = F.lds + RING_OFF; LAS unsigned char* VB0 = F.lds + RING_OFF + 32768;
;     bf16x8 qf[8];
;     { const bf16* qp = Qb + ((size_t)b * T + q0w + r32) * SBW + h * HD + 8 * hh;
; #pragma unroll
;       for (int s = 0; s < 8; ++s) qf[s] = *(const bf16x8*)(qp + 16 * s); }
;     const float k1 = SB_SCALE * LOG2E, k2 = kin(12)[h] * LOG2E;
;     f32x16 oacc[4];
; #pragma unroll
;     for (int d = 0; d < 4; ++d)
; #pragma unroll
;         for (int i = 0; i < 16; ++i) oacc[d][i] = 0.f;
;     float R = 1.f;
;     const int nt = 2 * qb + 2, ktop = (half == 0) ? 4 * qb + 3 : 2 * qb + 1;
;     const int srow = F.tid >> 4, sch = F.tid & 15;
;     const size_t gbase = ((size_t)b * T) * SBW + h * HD + sch * 8;
;     v4u rk[2], rv[2];
;     ...
;     const unsigned kwo = (unsigned)((sch >> 1) * 1024 + srow * 32 + (((sch & 1) ^ ((srow >> 3) & 1)) * 16));
;     const unsigned vwo = (unsigned)((((srow >> 3) * 4 + (sch >> 2)) * 512) + (srow & 7) * 64 + (sch & 3) * 16);
;     ...
;     SB_LOAD(64 * ktop); SB_WRITE(0);
;     __syncthreads();
; __device__ __forceinline__ void p2_mixers(Frame& F, unsigned* qctr) {
;     ...
;           const int qb = 15 - (cur >> 5), hf = (cur >> 4) & 1, bh = cur & 15;
;           sb_attn_unit(F, bh >> 3, bh & 7, qb, hf);
.LBB0_1431:
	s_or_b64 exec, exec, s[10:11]
	s_and_b32 s12, s96, 7
	s_lshr_b32 s13, s2, 2
	s_lshl_b32 s13, s13, 5
	s_or_b32 s12, s12, s13
	s_bfe_u32 s13, s2, 0x10001
	s_lshl_b32 s13, s13, 4
	s_or_b32 s12, s12, s13
	s_and_b32 s13, s2, 1
	s_lshl_b32 s13, s13, 3
	s_or_b32 s2, s12, s13
	s_ashr_i32 s12, s2, 5
	s_sub_i32 s30, 15, s12
	s_lshl_b32 s35, s30, 8
	s_bfe_u32 s33, s2, 0x10003
	s_add_i32 s35, s35, s40
	s_bfe_u32 s29, s2, 0x10004
	s_and_b32 s31, s2, 7
	s_lshl_b32 s2, s33, 12
	s_ashr_i32 s10, s35, 31
	s_add_u32 s2, s35, s2
	s_addc_u32 s10, s10, 0
	v_mov_b32_e32 v5, s10
	v_or_b32_e32 v4, s2, v182
	v_lshlrev_b64 v[4:5], 11, v[4:5]
	v_lshl_add_u64 v[4:5], s[46:47], 0, v[4:5]
	s_lshl_b32 s44, s31, 8
	v_lshl_add_u64 v[4:5], v[4:5], 0, s[44:45]
	v_lshl_add_u64 v[4:5], v[4:5], 0, v[154:155]
	s_movk_i32 s2, 0x60
	global_load_dwordx4 v[142:145], v[4:5], off
	global_load_dwordx4 v[138:141], v[4:5], off offset:32
	global_load_dwordx4 v[134:137], v[4:5], off offset:64
	global_load_dwordx4 v[130:133], v[4:5], off offset:96
	global_load_dwordx4 v[126:129], v[4:5], off offset:128
	global_load_dwordx4 v[122:125], v[4:5], off offset:160
	global_load_dwordx4 v[118:121], v[4:5], off offset:192
	global_load_dwordx4 v[114:117], v[4:5], off offset:224
	s_lshl_b32 s13, s30, 1
	s_lshl_b32 s14, s30, 2
	s_load_dwordx2 s[10:11], s[0:1], s2 offset:0x0
	s_lshl_b32 s2, s31, 2
	s_or_b32 s14, s14, 3
	s_or_b32 s13, s13, 1
	s_cmp_eq_u32 s29, 0
	s_cselect_b32 s36, s14, s13
	v_lshl_or_b32 v2, s33, 22, v150
	s_lshl_b32 s13, s36, 6
	v_lshl_or_b32 v160, s31, 7, v2
	v_or_b32_e32 v2, s13, v157
	v_mov_b32_e32 v161, v1
	v_lshlrev_b64 v[4:5], 10, v[2:3]
	v_lshl_add_u64 v[4:5], v[4:5], 0, v[160:161]
	v_lshlrev_b64 v[4:5], 1, v[4:5]
	v_lshl_add_u64 v[6:7], s[48:49], 0, v[4:5]
	v_lshl_add_u64 v[4:5], s[50:51], 0, v[4:5]
	v_or_b32_e32 v2, 32, v2
	global_load_dwordx4 v[66:69], v[6:7], off
	global_load_dwordx4 v[70:73], v[4:5], off
	v_lshlrev_b64 v[4:5], 10, v[2:3]
	v_lshl_add_u64 v[4:5], v[4:5], 0, v[160:161]
	v_lshlrev_b64 v[4:5], 1, v[4:5]
	v_lshl_add_u64 v[6:7], s[48:49], 0, v[4:5]
	v_lshl_add_u64 v[4:5], s[50:51], 0, v[4:5]
	global_load_dwordx4 v[74:77], v[6:7], off
	global_load_dwordx4 v[78:81], v[4:5], off
	v_mov_b32_e32 v2, s2
	s_waitcnt lgkmcnt(0)
	global_load_dword v82, v2, s[10:11]
	s_sub_i32 s98, s13, 64
	v_add_u32_e32 v240, s98, v157
	v_add_u32_e32 v242, 32, v240
	v_ashrrev_i32_e32 v241, 31, v240
	v_ashrrev_i32_e32 v243, 31, v242
	v_lshlrev_b64 v[240:241], 10, v[240:241]
	v_lshlrev_b64 v[242:243], 10, v[242:243]
	v_lshl_add_u64 v[240:241], v[240:241], 0, v[160:161]
	v_lshl_add_u64 v[242:243], v[242:243], 0, v[160:161]
	v_lshlrev_b64 v[240:241], 1, v[240:241]
	v_lshlrev_b64 v[242:243], 1, v[242:243]
	v_lshl_add_u64 v[244:245], s[48:49], 0, v[240:241]
	v_lshl_add_u64 v[246:247], s[50:51], 0, v[240:241]
	v_lshl_add_u64 v[248:249], s[48:49], 0, v[242:243]
	v_lshl_add_u64 v[240:241], s[50:51], 0, v[242:243]
	global_load_dwordx4 v[222:225], v[244:245], off
	global_load_dwordx4 v[226:229], v[246:247], off
	global_load_dwordx4 v[230:233], v[248:249], off
	global_load_dwordx4 v[234:237], v[240:241], off
	v_mov_b32_e32 v16, v3
	v_mov_b32_e32 v17, v3
	v_mov_b32_e32 v4, v3
	v_mov_b32_e32 v5, v3
	v_mov_b32_e32 v6, v3
	v_mov_b32_e32 v7, v3
	v_mov_b32_e32 v8, v3
	v_mov_b32_e32 v9, v3
	v_mov_b32_e32 v10, v3
	v_mov_b32_e32 v11, v3
	v_mov_b32_e32 v12, v3
	v_mov_b32_e32 v13, v3
	v_mov_b32_e32 v14, v3
	v_mov_b32_e32 v15, v3
	v_or_b32_e32 v156, s35, v182
	s_lshl_b32 s2, s12, 1
	v_mov_b32_e32 v2, v3
	v_mov_b64_e32 v[32:33], v[16:17]
	v_mov_b64_e32 v[48:49], v[16:17]
	v_mov_b64_e32 v[64:65], v[16:17]
	s_mov_b32 s37, 0
	v_mov_b32_e32 v159, 1.0
	v_mov_b32_e32 v151, v156
	s_or_b32 s44, s35, 31
	s_sub_i32 s41, 31, s2
	s_or_b32 s52, s13, 63
	v_mov_b64_e32 v[30:31], v[14:15]
	v_mov_b64_e32 v[28:29], v[12:13]
	v_mov_b64_e32 v[26:27], v[10:11]
	v_mov_b64_e32 v[24:25], v[8:9]
	v_mov_b64_e32 v[22:23], v[6:7]
	v_mov_b64_e32 v[20:21], v[4:5]
	v_mov_b64_e32 v[18:19], v[2:3]
	v_mov_b64_e32 v[46:47], v[14:15]
	v_mov_b64_e32 v[44:45], v[12:13]
	v_mov_b64_e32 v[42:43], v[10:11]
	v_mov_b64_e32 v[40:41], v[8:9]
	v_mov_b64_e32 v[38:39], v[6:7]
	v_mov_b64_e32 v[36:37], v[4:5]
	v_mov_b64_e32 v[34:35], v[2:3]
	v_mov_b64_e32 v[62:63], v[14:15]
	v_mov_b64_e32 v[60:61], v[12:13]
	v_mov_b64_e32 v[58:59], v[10:11]
	v_mov_b64_e32 v[56:57], v[8:9]
	v_mov_b64_e32 v[54:55], v[6:7]
	v_mov_b64_e32 v[52:53], v[4:5]
	v_mov_b64_e32 v[50:51], v[2:3]
	s_waitcnt vmcnt(8)
	ds_write_b128 v162, v[66:69]
	s_waitcnt vmcnt(7)
	ds_write_b128 v163, v[70:73] offset:32768
	s_waitcnt vmcnt(6)
	ds_write_b128 v162, v[74:77] offset:8192
	s_waitcnt vmcnt(5)
	ds_write_b128 v163, v[78:81] offset:40960
	v_mov_b64_e32 v[80:81], v[16:17]
	s_waitcnt vmcnt(4)
	v_mul_f32_e32 v170, 0x3fb8aa3b, v82
	v_mov_b64_e32 v[78:79], v[14:15]
	v_mov_b64_e32 v[76:77], v[12:13]
	v_mov_b64_e32 v[74:75], v[10:11]
	v_mov_b64_e32 v[72:73], v[8:9]
	v_mov_b64_e32 v[70:71], v[6:7]
	v_mov_b64_e32 v[68:69], v[4:5]
	v_mov_b64_e32 v[66:67], v[2:3]
	s_waitcnt lgkmcnt(0)
	s_barrier
	s_branch .LBB0_1434
